# up epilogue: edge taps built by v_mov_b32_dpp into the exchanged-row registers then packed FMAs; identity selects of context tiles skipped
# speedup vs baseline: 1.1111x; 1.0012x over previous
.LUPE_noex:
	ds_read_b128 v[172:175], v226
	ds_read_b128 v[176:179], v226 offset:128
	ds_read_b128 v[180:183], v226 offset:256
	ds_read_b128 v[184:187], v226 offset:384
	s_waitcnt vmcnt(0) lgkmcnt(0)
	v_cndmask_b32_e64 v172, 0, v172, s[52:53]
	v_cndmask_b32_e64 v173, 0, v173, s[52:53]
	v_cndmask_b32_e64 v174, 0, v174, s[52:53]
	v_cndmask_b32_e64 v175, 0, v175, s[52:53]
	v_cndmask_b32_e64 v176, 0, v176, s[52:53]
	v_cndmask_b32_e64 v177, 0, v177, s[52:53]
	v_cndmask_b32_e64 v178, 0, v178, s[52:53]
	v_cndmask_b32_e64 v179, 0, v179, s[52:53]
	s_cbranch_vccnz .LUPE_sel1
	v_cndmask_b32_e32 v180, 0, v180, vcc
	v_cndmask_b32_e32 v181, 0, v181, vcc
	v_cndmask_b32_e32 v182, 0, v182, vcc
	v_cndmask_b32_e32 v183, 0, v183, vcc
	v_cndmask_b32_e32 v184, 0, v184, vcc
	v_cndmask_b32_e32 v185, 0, v185, vcc
	v_cndmask_b32_e32 v186, 0, v186, vcc
	v_cndmask_b32_e32 v187, 0, v187, vcc
.LUPE_sel1:
	v_pk_fma_f32 v[228:229], v[136:137], v[116:117], v[140:141]
	v_pk_fma_f32 v[230:231], v[138:139], v[118:119], v[142:143]
	v_pk_fma_f32 v[232:233], v[152:153], v[112:113], v[156:157]
	v_pk_fma_f32 v[234:235], v[154:155], v[114:115], v[158:159]
	v_pk_fma_f32 v[228:229], v[132:133], v[124:125], v[228:229]
	v_pk_fma_f32 v[230:231], v[134:135], v[126:127], v[230:231]
	v_pk_fma_f32 v[232:233], v[148:149], v[120:121], v[232:233]
	v_pk_fma_f32 v[234:235], v[150:151], v[122:123], v[234:235]
	v_mov_b32_dpp v172, v100 row_shr:1 row_mask:0xf bank_mask:0xf
	v_mov_b32_dpp v173, v101 row_shr:1 row_mask:0xf bank_mask:0xf
	v_mov_b32_dpp v174, v102 row_shr:1 row_mask:0xf bank_mask:0xf
	v_mov_b32_dpp v175, v103 row_shr:1 row_mask:0xf bank_mask:0xf
	v_mov_b32_dpp v176, v96 row_shr:1 row_mask:0xf bank_mask:0xf
	v_mov_b32_dpp v177, v97 row_shr:1 row_mask:0xf bank_mask:0xf
	v_mov_b32_dpp v178, v98 row_shr:1 row_mask:0xf bank_mask:0xf
	v_mov_b32_dpp v179, v99 row_shr:1 row_mask:0xf bank_mask:0xf
	v_pk_fma_f32 v[228:229], v[128:129], v[172:173], v[228:229]
	v_pk_fma_f32 v[230:231], v[130:131], v[174:175], v[230:231]
	v_pk_fma_f32 v[232:233], v[144:145], v[176:177], v[232:233]
	v_pk_fma_f32 v[234:235], v[146:147], v[178:179], v[234:235]
	v_pk_mul_f32 v[216:217], v[228:229], v[220:221]
	v_pk_mul_f32 v[218:219], v[230:231], v[220:221]
	v_exp_f32_e32 v216, v216
	v_exp_f32_e32 v217, v217
	v_exp_f32_e32 v218, v218
	v_exp_f32_e32 v219, v219
	v_pk_add_f32 v[216:217], v[216:217], v[222:223]
	v_pk_add_f32 v[218:219], v[218:219], v[222:223]
	v_rcp_f32_e32 v216, v216
	v_rcp_f32_e32 v217, v217
	v_rcp_f32_e32 v218, v218
	v_rcp_f32_e32 v219, v219
	v_pk_mul_f32 v[228:229], v[228:229], v[216:217]
	v_pk_mul_f32 v[230:231], v[230:231], v[218:219]
	v_pk_mul_f32 v[228:229], v[232:233], v[228:229]
	v_pk_mul_f32 v[230:231], v[234:235], v[230:231]
	s_mov_b64 s[8:9], s[90:91]
	v_cvt_pk_bf16_f32 v224, v228, v229
	v_cvt_pk_bf16_f32 v225, v230, v231
	global_store_dwordx2 v237, v[224:225], s[8:9]
	ds_read_b128 v[172:175], v226 offset:512
	ds_read_b128 v[176:179], v226 offset:640
	v_pk_fma_f32 v[228:229], v[136:137], v[108:109], v[140:141]
	v_pk_fma_f32 v[230:231], v[138:139], v[110:111], v[142:143]
	v_pk_fma_f32 v[232:233], v[152:153], v[104:105], v[156:157]
	v_pk_fma_f32 v[234:235], v[154:155], v[106:107], v[158:159]
	v_pk_fma_f32 v[228:229], v[132:133], v[116:117], v[228:229]
	v_pk_fma_f32 v[230:231], v[134:135], v[118:119], v[230:231]
	v_pk_fma_f32 v[232:233], v[148:149], v[112:113], v[232:233]
	v_pk_fma_f32 v[234:235], v[150:151], v[114:115], v[234:235]
	v_pk_fma_f32 v[228:229], v[128:129], v[124:125], v[228:229]
	v_pk_fma_f32 v[230:231], v[130:131], v[126:127], v[230:231]
	v_pk_fma_f32 v[232:233], v[144:145], v[120:121], v[232:233]
	v_pk_fma_f32 v[234:235], v[146:147], v[122:123], v[234:235]
	v_pk_mul_f32 v[216:217], v[228:229], v[220:221]
	v_pk_mul_f32 v[218:219], v[230:231], v[220:221]
	v_exp_f32_e32 v216, v216
	v_exp_f32_e32 v217, v217
	v_exp_f32_e32 v218, v218
	v_exp_f32_e32 v219, v219
	v_pk_add_f32 v[216:217], v[216:217], v[222:223]
	v_pk_add_f32 v[218:219], v[218:219], v[222:223]
	v_rcp_f32_e32 v216, v216
	v_rcp_f32_e32 v217, v217
	v_rcp_f32_e32 v218, v218
	v_rcp_f32_e32 v219, v219
	v_pk_mul_f32 v[228:229], v[228:229], v[216:217]
	v_pk_mul_f32 v[230:231], v[230:231], v[218:219]
	v_pk_mul_f32 v[228:229], v[232:233], v[228:229]
	v_pk_mul_f32 v[230:231], v[234:235], v[230:231]
	s_add_u32 s8, s90, 0x1600
	s_addc_u32 s9, s91, 0
	v_cvt_pk_bf16_f32 v224, v228, v229
	v_cvt_pk_bf16_f32 v225, v230, v231
	global_store_dwordx2 v237, v[224:225], s[8:9]
	v_pk_fma_f32 v[228:229], v[136:137], v[100:101], v[140:141]
	v_pk_fma_f32 v[230:231], v[138:139], v[102:103], v[142:143]
	v_pk_fma_f32 v[232:233], v[152:153], v[96:97], v[156:157]
	v_pk_fma_f32 v[234:235], v[154:155], v[98:99], v[158:159]
	v_pk_fma_f32 v[228:229], v[132:133], v[108:109], v[228:229]
	v_pk_fma_f32 v[230:231], v[134:135], v[110:111], v[230:231]
	v_pk_fma_f32 v[232:233], v[148:149], v[104:105], v[232:233]
	v_pk_fma_f32 v[234:235], v[150:151], v[106:107], v[234:235]
	v_pk_fma_f32 v[228:229], v[128:129], v[116:117], v[228:229]
	v_pk_fma_f32 v[230:231], v[130:131], v[118:119], v[230:231]
	v_pk_fma_f32 v[232:233], v[144:145], v[112:113], v[232:233]
	v_pk_fma_f32 v[234:235], v[146:147], v[114:115], v[234:235]
	v_pk_mul_f32 v[216:217], v[228:229], v[220:221]
	v_pk_mul_f32 v[218:219], v[230:231], v[220:221]
	v_exp_f32_e32 v216, v216
	v_exp_f32_e32 v217, v217
	v_exp_f32_e32 v218, v218
	v_exp_f32_e32 v219, v219
	v_pk_add_f32 v[216:217], v[216:217], v[222:223]
	v_pk_add_f32 v[218:219], v[218:219], v[222:223]
	v_rcp_f32_e32 v216, v216
	v_rcp_f32_e32 v217, v217
	v_rcp_f32_e32 v218, v218
	v_rcp_f32_e32 v219, v219
	v_pk_mul_f32 v[228:229], v[228:229], v[216:217]
	v_pk_mul_f32 v[230:231], v[230:231], v[218:219]
	v_pk_mul_f32 v[228:229], v[232:233], v[228:229]
	v_pk_mul_f32 v[230:231], v[234:235], v[230:231]
	s_add_u32 s8, s90, 0x2c00
	s_addc_u32 s9, s91, 0
	v_cvt_pk_bf16_f32 v224, v228, v229
	v_cvt_pk_bf16_f32 v225, v230, v231
	global_store_dwordx2 v237, v[224:225], s[8:9]
	v_mov_b32_dpp v180, v124 row_shl:1 row_mask:0xf bank_mask:0xf
	v_mov_b32_dpp v181, v125 row_shl:1 row_mask:0xf bank_mask:0xf
	v_mov_b32_dpp v182, v126 row_shl:1 row_mask:0xf bank_mask:0xf
	v_mov_b32_dpp v183, v127 row_shl:1 row_mask:0xf bank_mask:0xf
	v_mov_b32_dpp v184, v120 row_shl:1 row_mask:0xf bank_mask:0xf
	v_mov_b32_dpp v185, v121 row_shl:1 row_mask:0xf bank_mask:0xf
	v_mov_b32_dpp v186, v122 row_shl:1 row_mask:0xf bank_mask:0xf
	v_mov_b32_dpp v187, v123 row_shl:1 row_mask:0xf bank_mask:0xf
	v_pk_fma_f32 v[228:229], v[136:137], v[180:181], v[140:141]
	v_pk_fma_f32 v[230:231], v[138:139], v[182:183], v[142:143]
	v_pk_fma_f32 v[232:233], v[152:153], v[184:185], v[156:157]
	v_pk_fma_f32 v[234:235], v[154:155], v[186:187], v[158:159]
	ds_read_b128 v[180:183], v226 offset:768
	ds_read_b128 v[184:187], v226 offset:896
	v_pk_fma_f32 v[228:229], v[132:133], v[100:101], v[228:229]
	v_pk_fma_f32 v[230:231], v[134:135], v[102:103], v[230:231]
	v_pk_fma_f32 v[232:233], v[148:149], v[96:97], v[232:233]
	v_pk_fma_f32 v[234:235], v[150:151], v[98:99], v[234:235]
	v_pk_fma_f32 v[228:229], v[128:129], v[108:109], v[228:229]
	v_pk_fma_f32 v[230:231], v[130:131], v[110:111], v[230:231]
	v_pk_fma_f32 v[232:233], v[144:145], v[104:105], v[232:233]
	v_pk_fma_f32 v[234:235], v[146:147], v[106:107], v[234:235]
	v_pk_mul_f32 v[216:217], v[228:229], v[220:221]
	v_pk_mul_f32 v[218:219], v[230:231], v[220:221]
	v_exp_f32_e32 v216, v216
	v_exp_f32_e32 v217, v217
	v_exp_f32_e32 v218, v218
	v_exp_f32_e32 v219, v219
	v_pk_add_f32 v[216:217], v[216:217], v[222:223]
	v_pk_add_f32 v[218:219], v[218:219], v[222:223]
	v_rcp_f32_e32 v216, v216
	v_rcp_f32_e32 v217, v217
	v_rcp_f32_e32 v218, v218
	v_rcp_f32_e32 v219, v219
	v_pk_mul_f32 v[228:229], v[228:229], v[216:217]
	v_pk_mul_f32 v[230:231], v[230:231], v[218:219]
	v_pk_mul_f32 v[228:229], v[232:233], v[228:229]
	v_pk_mul_f32 v[230:231], v[234:235], v[230:231]
	s_add_u32 s8, s90, 0x4200
	s_addc_u32 s9, s91, 0
	v_cvt_pk_bf16_f32 v224, v228, v229
	v_cvt_pk_bf16_f32 v225, v230, v231
	global_store_dwordx2 v237, v[224:225], s[8:9]
	global_load_dwordx4 v[96:99], v227, s[76:77] offset:16
	global_load_dwordx4 v[112:115], v236, s[76:77] offset:16
	global_load_dwordx4 v[100:103], v227, s[80:81] offset:16
	global_load_dwordx4 v[116:119], v236, s[80:81] offset:16
	global_load_dwordx4 v[104:107], v227, s[86:87] offset:16
	global_load_dwordx4 v[120:123], v236, s[86:87] offset:16
	global_load_dwordx4 v[108:111], v227, s[4:5] offset:16
	global_load_dwordx4 v[124:127], v236, s[4:5] offset:16
	s_waitcnt lgkmcnt(0)
	s_cbranch_vccnz .LUPE_sel2
	v_cndmask_b32_e32 v172, 0, v172, vcc
	v_cndmask_b32_e32 v173, 0, v173, vcc
	v_cndmask_b32_e32 v174, 0, v174, vcc
	v_cndmask_b32_e32 v175, 0, v175, vcc
	v_cndmask_b32_e32 v176, 0, v176, vcc
	v_cndmask_b32_e32 v177, 0, v177, vcc
	v_cndmask_b32_e32 v178, 0, v178, vcc
	v_cndmask_b32_e32 v179, 0, v179, vcc
.LUPE_sel2:
	v_cndmask_b32_e64 v180, 0, v180, s[68:69]
	v_cndmask_b32_e64 v181, 0, v181, s[68:69]
	v_cndmask_b32_e64 v182, 0, v182, s[68:69]
	v_cndmask_b32_e64 v183, 0, v183, s[68:69]
	v_cndmask_b32_e64 v184, 0, v184, s[68:69]
	v_cndmask_b32_e64 v185, 0, v185, s[68:69]
	v_cndmask_b32_e64 v186, 0, v186, s[68:69]
	v_cndmask_b32_e64 v187, 0, v187, s[68:69]
	v_pk_fma_f32 v[228:229], v[136:137], v[84:85], v[140:141]
	v_pk_fma_f32 v[230:231], v[138:139], v[86:87], v[142:143]
	v_pk_fma_f32 v[232:233], v[152:153], v[80:81], v[156:157]
	v_pk_fma_f32 v[234:235], v[154:155], v[82:83], v[158:159]
	v_pk_fma_f32 v[228:229], v[132:133], v[92:93], v[228:229]
	v_pk_fma_f32 v[230:231], v[134:135], v[94:95], v[230:231]
	v_pk_fma_f32 v[232:233], v[148:149], v[88:89], v[232:233]
	v_pk_fma_f32 v[234:235], v[150:151], v[90:91], v[234:235]
	v_mov_b32_dpp v172, v72 row_shr:1 row_mask:0xf bank_mask:0xf
	v_mov_b32_dpp v173, v73 row_shr:1 row_mask:0xf bank_mask:0xf
	v_mov_b32_dpp v174, v74 row_shr:1 row_mask:0xf bank_mask:0xf
	v_mov_b32_dpp v175, v75 row_shr:1 row_mask:0xf bank_mask:0xf
	v_mov_b32_dpp v176, v64 row_shr:1 row_mask:0xf bank_mask:0xf
	v_mov_b32_dpp v177, v65 row_shr:1 row_mask:0xf bank_mask:0xf
	v_mov_b32_dpp v178, v66 row_shr:1 row_mask:0xf bank_mask:0xf
	v_mov_b32_dpp v179, v67 row_shr:1 row_mask:0xf bank_mask:0xf
	v_pk_fma_f32 v[228:229], v[128:129], v[172:173], v[228:229]
	v_pk_fma_f32 v[230:231], v[130:131], v[174:175], v[230:231]
	v_pk_fma_f32 v[232:233], v[144:145], v[176:177], v[232:233]
	v_pk_fma_f32 v[234:235], v[146:147], v[178:179], v[234:235]
	v_pk_mul_f32 v[216:217], v[228:229], v[220:221]
	v_pk_mul_f32 v[218:219], v[230:231], v[220:221]
	v_exp_f32_e32 v216, v216
	v_exp_f32_e32 v217, v217
	v_exp_f32_e32 v218, v218
	v_exp_f32_e32 v219, v219
	v_pk_add_f32 v[216:217], v[216:217], v[222:223]
	v_pk_add_f32 v[218:219], v[218:219], v[222:223]
	v_rcp_f32_e32 v216, v216
	v_rcp_f32_e32 v217, v217
	v_rcp_f32_e32 v218, v218
	v_rcp_f32_e32 v219, v219
	v_pk_mul_f32 v[228:229], v[228:229], v[216:217]
	v_pk_mul_f32 v[230:231], v[230:231], v[218:219]
	v_pk_mul_f32 v[228:229], v[232:233], v[228:229]
	v_pk_mul_f32 v[230:231], v[234:235], v[230:231]
	s_add_u32 s8, s90, 0xb0000
	s_addc_u32 s9, s91, 0
	v_cvt_pk_bf16_f32 v224, v228, v229
	v_cvt_pk_bf16_f32 v225, v230, v231
	global_store_dwordx2 v237, v[224:225], s[8:9]
	ds_read_b128 v[172:175], v226 offset:64
	ds_read_b128 v[176:179], v226 offset:192
	v_pk_fma_f32 v[228:229], v[136:137], v[76:77], v[140:141]
	v_pk_fma_f32 v[230:231], v[138:139], v[78:79], v[142:143]
	v_pk_fma_f32 v[232:233], v[152:153], v[68:69], v[156:157]
	v_pk_fma_f32 v[234:235], v[154:155], v[70:71], v[158:159]
	v_pk_fma_f32 v[228:229], v[132:133], v[84:85], v[228:229]
	v_pk_fma_f32 v[230:231], v[134:135], v[86:87], v[230:231]
	v_pk_fma_f32 v[232:233], v[148:149], v[80:81], v[232:233]
	v_pk_fma_f32 v[234:235], v[150:151], v[82:83], v[234:235]
	v_pk_fma_f32 v[228:229], v[128:129], v[92:93], v[228:229]
	v_pk_fma_f32 v[230:231], v[130:131], v[94:95], v[230:231]
	v_pk_fma_f32 v[232:233], v[144:145], v[88:89], v[232:233]
	v_pk_fma_f32 v[234:235], v[146:147], v[90:91], v[234:235]
	v_pk_mul_f32 v[216:217], v[228:229], v[220:221]
	v_pk_mul_f32 v[218:219], v[230:231], v[220:221]
	v_exp_f32_e32 v216, v216
	v_exp_f32_e32 v217, v217
	v_exp_f32_e32 v218, v218
	v_exp_f32_e32 v219, v219
	v_pk_add_f32 v[216:217], v[216:217], v[222:223]
	v_pk_add_f32 v[218:219], v[218:219], v[222:223]
	v_rcp_f32_e32 v216, v216
	v_rcp_f32_e32 v217, v217
	v_rcp_f32_e32 v218, v218
	v_rcp_f32_e32 v219, v219
	v_pk_mul_f32 v[228:229], v[228:229], v[216:217]
	v_pk_mul_f32 v[230:231], v[230:231], v[218:219]
	v_pk_mul_f32 v[228:229], v[232:233], v[228:229]
	v_pk_mul_f32 v[230:231], v[234:235], v[230:231]
	s_add_u32 s8, s90, 0xb1600
	s_addc_u32 s9, s91, 0
	v_cvt_pk_bf16_f32 v224, v228, v229
	v_cvt_pk_bf16_f32 v225, v230, v231
	global_store_dwordx2 v237, v[224:225], s[8:9]
	v_pk_fma_f32 v[228:229], v[136:137], v[72:73], v[140:141]
	v_pk_fma_f32 v[230:231], v[138:139], v[74:75], v[142:143]
	v_pk_fma_f32 v[232:233], v[152:153], v[64:65], v[156:157]
	v_pk_fma_f32 v[234:235], v[154:155], v[66:67], v[158:159]
	v_pk_fma_f32 v[228:229], v[132:133], v[76:77], v[228:229]
	v_pk_fma_f32 v[230:231], v[134:135], v[78:79], v[230:231]
	v_pk_fma_f32 v[232:233], v[148:149], v[68:69], v[232:233]
	v_pk_fma_f32 v[234:235], v[150:151], v[70:71], v[234:235]
	v_pk_fma_f32 v[228:229], v[128:129], v[84:85], v[228:229]
	v_pk_fma_f32 v[230:231], v[130:131], v[86:87], v[230:231]
	v_pk_fma_f32 v[232:233], v[144:145], v[80:81], v[232:233]
	v_pk_fma_f32 v[234:235], v[146:147], v[82:83], v[234:235]
	v_pk_mul_f32 v[216:217], v[228:229], v[220:221]
	v_pk_mul_f32 v[218:219], v[230:231], v[220:221]
	v_exp_f32_e32 v216, v216
	v_exp_f32_e32 v217, v217
	v_exp_f32_e32 v218, v218
	v_exp_f32_e32 v219, v219
	v_pk_add_f32 v[216:217], v[216:217], v[222:223]
	v_pk_add_f32 v[218:219], v[218:219], v[222:223]
	v_rcp_f32_e32 v216, v216
	v_rcp_f32_e32 v217, v217
	v_rcp_f32_e32 v218, v218
	v_rcp_f32_e32 v219, v219
	v_pk_mul_f32 v[228:229], v[228:229], v[216:217]
	v_pk_mul_f32 v[230:231], v[230:231], v[218:219]
	v_pk_mul_f32 v[228:229], v[232:233], v[228:229]
	v_pk_mul_f32 v[230:231], v[234:235], v[230:231]
	s_add_u32 s8, s90, 0xb2c00
	s_addc_u32 s9, s91, 0
	v_cvt_pk_bf16_f32 v224, v228, v229
	v_cvt_pk_bf16_f32 v225, v230, v231
	global_store_dwordx2 v237, v[224:225], s[8:9]
	v_mov_b32_dpp v180, v92 row_shl:1 row_mask:0xf bank_mask:0xf
	v_mov_b32_dpp v181, v93 row_shl:1 row_mask:0xf bank_mask:0xf
	v_mov_b32_dpp v182, v94 row_shl:1 row_mask:0xf bank_mask:0xf
	v_mov_b32_dpp v183, v95 row_shl:1 row_mask:0xf bank_mask:0xf
	v_mov_b32_dpp v184, v88 row_shl:1 row_mask:0xf bank_mask:0xf
	v_mov_b32_dpp v185, v89 row_shl:1 row_mask:0xf bank_mask:0xf
	v_mov_b32_dpp v186, v90 row_shl:1 row_mask:0xf bank_mask:0xf
	v_mov_b32_dpp v187, v91 row_shl:1 row_mask:0xf bank_mask:0xf
	v_pk_fma_f32 v[228:229], v[136:137], v[180:181], v[140:141]
	v_pk_fma_f32 v[230:231], v[138:139], v[182:183], v[142:143]
	v_pk_fma_f32 v[232:233], v[152:153], v[184:185], v[156:157]
	v_pk_fma_f32 v[234:235], v[154:155], v[186:187], v[158:159]
	ds_read_b128 v[180:183], v226 offset:320
	ds_read_b128 v[184:187], v226 offset:448
	v_pk_fma_f32 v[228:229], v[132:133], v[72:73], v[228:229]
	v_pk_fma_f32 v[230:231], v[134:135], v[74:75], v[230:231]
	v_pk_fma_f32 v[232:233], v[148:149], v[64:65], v[232:233]
	v_pk_fma_f32 v[234:235], v[150:151], v[66:67], v[234:235]
	v_pk_fma_f32 v[228:229], v[128:129], v[76:77], v[228:229]
	v_pk_fma_f32 v[230:231], v[130:131], v[78:79], v[230:231]
	v_pk_fma_f32 v[232:233], v[144:145], v[68:69], v[232:233]
	v_pk_fma_f32 v[234:235], v[146:147], v[70:71], v[234:235]
	v_pk_mul_f32 v[216:217], v[228:229], v[220:221]
	v_pk_mul_f32 v[218:219], v[230:231], v[220:221]
	v_exp_f32_e32 v216, v216
	v_exp_f32_e32 v217, v217
	v_exp_f32_e32 v218, v218
	v_exp_f32_e32 v219, v219
	v_pk_add_f32 v[216:217], v[216:217], v[222:223]
	v_pk_add_f32 v[218:219], v[218:219], v[222:223]
	v_rcp_f32_e32 v216, v216
	v_rcp_f32_e32 v217, v217
	v_rcp_f32_e32 v218, v218
	v_rcp_f32_e32 v219, v219
	v_pk_mul_f32 v[228:229], v[228:229], v[216:217]
	v_pk_mul_f32 v[230:231], v[230:231], v[218:219]
	v_pk_mul_f32 v[228:229], v[232:233], v[228:229]
	v_pk_mul_f32 v[230:231], v[234:235], v[230:231]
	s_add_u32 s8, s90, 0xb4200
	s_addc_u32 s9, s91, 0
	v_cvt_pk_bf16_f32 v224, v228, v229
	v_cvt_pk_bf16_f32 v225, v230, v231
	global_store_dwordx2 v237, v[224:225], s[8:9]
	s_waitcnt vmcnt(4) lgkmcnt(0)
	v_cndmask_b32_e64 v172, 0, v172, s[52:53]
	v_cndmask_b32_e64 v173, 0, v173, s[52:53]
	v_cndmask_b32_e64 v174, 0, v174, s[52:53]
	v_cndmask_b32_e64 v175, 0, v175, s[52:53]
	v_cndmask_b32_e64 v176, 0, v176, s[52:53]
	v_cndmask_b32_e64 v177, 0, v177, s[52:53]
	v_cndmask_b32_e64 v178, 0, v178, s[52:53]
	v_cndmask_b32_e64 v179, 0, v179, s[52:53]
	s_cbranch_vccnz .LUPE_sel3
	v_cndmask_b32_e32 v180, 0, v180, vcc
	v_cndmask_b32_e32 v181, 0, v181, vcc
	v_cndmask_b32_e32 v182, 0, v182, vcc
	v_cndmask_b32_e32 v183, 0, v183, vcc
	v_cndmask_b32_e32 v184, 0, v184, vcc
	v_cndmask_b32_e32 v185, 0, v185, vcc
	v_cndmask_b32_e32 v186, 0, v186, vcc
	v_cndmask_b32_e32 v187, 0, v187, vcc
.LUPE_sel3:
	v_pk_fma_f32 v[228:229], v[104:105], v[52:53], v[108:109]
	v_pk_fma_f32 v[230:231], v[106:107], v[54:55], v[110:111]
	v_pk_fma_f32 v[232:233], v[120:121], v[48:49], v[124:125]
	v_pk_fma_f32 v[234:235], v[122:123], v[50:51], v[126:127]
	v_pk_fma_f32 v[228:229], v[100:101], v[60:61], v[228:229]
	v_pk_fma_f32 v[230:231], v[102:103], v[62:63], v[230:231]
	v_pk_fma_f32 v[232:233], v[116:117], v[56:57], v[232:233]
	v_pk_fma_f32 v[234:235], v[118:119], v[58:59], v[234:235]
	v_mov_b32_dpp v172, v36 row_shr:1 row_mask:0xf bank_mask:0xf
	v_mov_b32_dpp v173, v37 row_shr:1 row_mask:0xf bank_mask:0xf
	v_mov_b32_dpp v174, v38 row_shr:1 row_mask:0xf bank_mask:0xf
	v_mov_b32_dpp v175, v39 row_shr:1 row_mask:0xf bank_mask:0xf
	v_mov_b32_dpp v176, v32 row_shr:1 row_mask:0xf bank_mask:0xf
	v_mov_b32_dpp v177, v33 row_shr:1 row_mask:0xf bank_mask:0xf
	v_mov_b32_dpp v178, v34 row_shr:1 row_mask:0xf bank_mask:0xf
	v_mov_b32_dpp v179, v35 row_shr:1 row_mask:0xf bank_mask:0xf
	v_pk_fma_f32 v[228:229], v[96:97], v[172:173], v[228:229]
	v_pk_fma_f32 v[230:231], v[98:99], v[174:175], v[230:231]
	v_pk_fma_f32 v[232:233], v[112:113], v[176:177], v[232:233]
	v_pk_fma_f32 v[234:235], v[114:115], v[178:179], v[234:235]
	v_pk_mul_f32 v[216:217], v[228:229], v[220:221]
	v_pk_mul_f32 v[218:219], v[230:231], v[220:221]
	v_exp_f32_e32 v216, v216
	v_exp_f32_e32 v217, v217
	v_exp_f32_e32 v218, v218
	v_exp_f32_e32 v219, v219
	v_pk_add_f32 v[216:217], v[216:217], v[222:223]
	v_pk_add_f32 v[218:219], v[218:219], v[222:223]
	v_rcp_f32_e32 v216, v216
	v_rcp_f32_e32 v217, v217
	v_rcp_f32_e32 v218, v218
	v_rcp_f32_e32 v219, v219
	v_pk_mul_f32 v[228:229], v[228:229], v[216:217]
	v_pk_mul_f32 v[230:231], v[230:231], v[218:219]
	v_pk_mul_f32 v[228:229], v[232:233], v[228:229]
	v_pk_mul_f32 v[230:231], v[234:235], v[230:231]
	s_mov_b64 s[8:9], s[90:91]
	v_cvt_pk_bf16_f32 v224, v228, v229
	v_cvt_pk_bf16_f32 v225, v230, v231
	global_store_dwordx2 v237, v[224:225], s[8:9] offset:8
	ds_read_b128 v[172:175], v226 offset:576
	ds_read_b128 v[176:179], v226 offset:704
	v_pk_fma_f32 v[228:229], v[104:105], v[44:45], v[108:109]
	v_pk_fma_f32 v[230:231], v[106:107], v[46:47], v[110:111]
	v_pk_fma_f32 v[232:233], v[120:121], v[40:41], v[124:125]
	v_pk_fma_f32 v[234:235], v[122:123], v[42:43], v[126:127]
	v_pk_fma_f32 v[228:229], v[100:101], v[52:53], v[228:229]
	v_pk_fma_f32 v[230:231], v[102:103], v[54:55], v[230:231]
	v_pk_fma_f32 v[232:233], v[116:117], v[48:49], v[232:233]
	v_pk_fma_f32 v[234:235], v[118:119], v[50:51], v[234:235]
	v_pk_fma_f32 v[228:229], v[96:97], v[60:61], v[228:229]
	v_pk_fma_f32 v[230:231], v[98:99], v[62:63], v[230:231]
	v_pk_fma_f32 v[232:233], v[112:113], v[56:57], v[232:233]
	v_pk_fma_f32 v[234:235], v[114:115], v[58:59], v[234:235]
	v_pk_mul_f32 v[216:217], v[228:229], v[220:221]
	v_pk_mul_f32 v[218:219], v[230:231], v[220:221]
	v_exp_f32_e32 v216, v216
	v_exp_f32_e32 v217, v217
	v_exp_f32_e32 v218, v218
	v_exp_f32_e32 v219, v219
	v_pk_add_f32 v[216:217], v[216:217], v[222:223]
	v_pk_add_f32 v[218:219], v[218:219], v[222:223]
	v_rcp_f32_e32 v216, v216
	v_rcp_f32_e32 v217, v217
	v_rcp_f32_e32 v218, v218
	v_rcp_f32_e32 v219, v219
	v_pk_mul_f32 v[228:229], v[228:229], v[216:217]
	v_pk_mul_f32 v[230:231], v[230:231], v[218:219]
	v_pk_mul_f32 v[228:229], v[232:233], v[228:229]
	v_pk_mul_f32 v[230:231], v[234:235], v[230:231]
	s_add_u32 s8, s90, 0x1600
	s_addc_u32 s9, s91, 0
	v_cvt_pk_bf16_f32 v224, v228, v229
	v_cvt_pk_bf16_f32 v225, v230, v231
	global_store_dwordx2 v237, v[224:225], s[8:9] offset:8
	v_pk_fma_f32 v[228:229], v[104:105], v[36:37], v[108:109]
	v_pk_fma_f32 v[230:231], v[106:107], v[38:39], v[110:111]
	v_pk_fma_f32 v[232:233], v[120:121], v[32:33], v[124:125]
	v_pk_fma_f32 v[234:235], v[122:123], v[34:35], v[126:127]
	v_pk_fma_f32 v[228:229], v[100:101], v[44:45], v[228:229]
	v_pk_fma_f32 v[230:231], v[102:103], v[46:47], v[230:231]
	v_pk_fma_f32 v[232:233], v[116:117], v[40:41], v[232:233]
	v_pk_fma_f32 v[234:235], v[118:119], v[42:43], v[234:235]
	v_pk_fma_f32 v[228:229], v[96:97], v[52:53], v[228:229]
	v_pk_fma_f32 v[230:231], v[98:99], v[54:55], v[230:231]
	v_pk_fma_f32 v[232:233], v[112:113], v[48:49], v[232:233]
	v_pk_fma_f32 v[234:235], v[114:115], v[50:51], v[234:235]
	v_pk_mul_f32 v[216:217], v[228:229], v[220:221]
	v_pk_mul_f32 v[218:219], v[230:231], v[220:221]
	v_exp_f32_e32 v216, v216
	v_exp_f32_e32 v217, v217
	v_exp_f32_e32 v218, v218
	v_exp_f32_e32 v219, v219
	v_pk_add_f32 v[216:217], v[216:217], v[222:223]
	v_pk_add_f32 v[218:219], v[218:219], v[222:223]
	v_rcp_f32_e32 v216, v216
	v_rcp_f32_e32 v217, v217
	v_rcp_f32_e32 v218, v218
	v_rcp_f32_e32 v219, v219
	v_pk_mul_f32 v[228:229], v[228:229], v[216:217]
	v_pk_mul_f32 v[230:231], v[230:231], v[218:219]
	v_pk_mul_f32 v[228:229], v[232:233], v[228:229]
	v_pk_mul_f32 v[230:231], v[234:235], v[230:231]
	s_add_u32 s8, s90, 0x2c00
	s_addc_u32 s9, s91, 0
	v_cvt_pk_bf16_f32 v224, v228, v229
	v_cvt_pk_bf16_f32 v225, v230, v231
	global_store_dwordx2 v237, v[224:225], s[8:9] offset:8
	v_mov_b32_dpp v180, v60 row_shl:1 row_mask:0xf bank_mask:0xf
	v_mov_b32_dpp v181, v61 row_shl:1 row_mask:0xf bank_mask:0xf
	v_mov_b32_dpp v182, v62 row_shl:1 row_mask:0xf bank_mask:0xf
	v_mov_b32_dpp v183, v63 row_shl:1 row_mask:0xf bank_mask:0xf
	v_mov_b32_dpp v184, v56 row_shl:1 row_mask:0xf bank_mask:0xf
	v_mov_b32_dpp v185, v57 row_shl:1 row_mask:0xf bank_mask:0xf
	v_mov_b32_dpp v186, v58 row_shl:1 row_mask:0xf bank_mask:0xf
	v_mov_b32_dpp v187, v59 row_shl:1 row_mask:0xf bank_mask:0xf
	v_pk_fma_f32 v[228:229], v[104:105], v[180:181], v[108:109]
	v_pk_fma_f32 v[230:231], v[106:107], v[182:183], v[110:111]
	v_pk_fma_f32 v[232:233], v[120:121], v[184:185], v[124:125]
	v_pk_fma_f32 v[234:235], v[122:123], v[186:187], v[126:127]
	ds_read_b128 v[180:183], v226 offset:832
	ds_read_b128 v[184:187], v226 offset:960
	v_pk_fma_f32 v[228:229], v[100:101], v[36:37], v[228:229]
	v_pk_fma_f32 v[230:231], v[102:103], v[38:39], v[230:231]
	v_pk_fma_f32 v[232:233], v[116:117], v[32:33], v[232:233]
	v_pk_fma_f32 v[234:235], v[118:119], v[34:35], v[234:235]
	v_pk_fma_f32 v[228:229], v[96:97], v[44:45], v[228:229]
	v_pk_fma_f32 v[230:231], v[98:99], v[46:47], v[230:231]
	v_pk_fma_f32 v[232:233], v[112:113], v[40:41], v[232:233]
	v_pk_fma_f32 v[234:235], v[114:115], v[42:43], v[234:235]
	v_pk_mul_f32 v[216:217], v[228:229], v[220:221]
	v_pk_mul_f32 v[218:219], v[230:231], v[220:221]
	v_exp_f32_e32 v216, v216
	v_exp_f32_e32 v217, v217
	v_exp_f32_e32 v218, v218
	v_exp_f32_e32 v219, v219
	v_pk_add_f32 v[216:217], v[216:217], v[222:223]
	v_pk_add_f32 v[218:219], v[218:219], v[222:223]
	v_rcp_f32_e32 v216, v216
	v_rcp_f32_e32 v217, v217
	v_rcp_f32_e32 v218, v218
	v_rcp_f32_e32 v219, v219
	v_pk_mul_f32 v[228:229], v[228:229], v[216:217]
	v_pk_mul_f32 v[230:231], v[230:231], v[218:219]
	v_pk_mul_f32 v[228:229], v[232:233], v[228:229]
	v_pk_mul_f32 v[230:231], v[234:235], v[230:231]
	s_add_u32 s8, s90, 0x4200
	s_addc_u32 s9, s91, 0
	v_cvt_pk_bf16_f32 v224, v228, v229
	v_cvt_pk_bf16_f32 v225, v230, v231
	global_store_dwordx2 v237, v[224:225], s[8:9] offset:8
	s_waitcnt lgkmcnt(0)
	s_cbranch_vccnz .LUPE_sel4
	v_cndmask_b32_e32 v172, 0, v172, vcc
	v_cndmask_b32_e32 v173, 0, v173, vcc
	v_cndmask_b32_e32 v174, 0, v174, vcc
	v_cndmask_b32_e32 v175, 0, v175, vcc
	v_cndmask_b32_e32 v176, 0, v176, vcc
	v_cndmask_b32_e32 v177, 0, v177, vcc
	v_cndmask_b32_e32 v178, 0, v178, vcc
	v_cndmask_b32_e32 v179, 0, v179, vcc
.LUPE_sel4:
	v_cndmask_b32_e64 v180, 0, v180, s[68:69]
	v_cndmask_b32_e64 v181, 0, v181, s[68:69]
	v_cndmask_b32_e64 v182, 0, v182, s[68:69]
	v_cndmask_b32_e64 v183, 0, v183, s[68:69]
	v_cndmask_b32_e64 v184, 0, v184, s[68:69]
	v_cndmask_b32_e64 v185, 0, v185, s[68:69]
	v_cndmask_b32_e64 v186, 0, v186, s[68:69]
	v_cndmask_b32_e64 v187, 0, v187, s[68:69]
	v_pk_fma_f32 v[228:229], v[104:105], v[20:21], v[108:109]
	v_pk_fma_f32 v[230:231], v[106:107], v[22:23], v[110:111]
	v_pk_fma_f32 v[232:233], v[120:121], v[16:17], v[124:125]
	v_pk_fma_f32 v[234:235], v[122:123], v[18:19], v[126:127]
	v_pk_fma_f32 v[228:229], v[100:101], v[28:29], v[228:229]
	v_pk_fma_f32 v[230:231], v[102:103], v[30:31], v[230:231]
	v_pk_fma_f32 v[232:233], v[116:117], v[24:25], v[232:233]
	v_pk_fma_f32 v[234:235], v[118:119], v[26:27], v[234:235]
	v_mov_b32_dpp v172, v4 row_shr:1 row_mask:0xf bank_mask:0xf
	v_mov_b32_dpp v173, v5 row_shr:1 row_mask:0xf bank_mask:0xf
	v_mov_b32_dpp v174, v6 row_shr:1 row_mask:0xf bank_mask:0xf
	v_mov_b32_dpp v175, v7 row_shr:1 row_mask:0xf bank_mask:0xf
	v_mov_b32_dpp v176, v0 row_shr:1 row_mask:0xf bank_mask:0xf
	v_mov_b32_dpp v177, v1 row_shr:1 row_mask:0xf bank_mask:0xf
	v_mov_b32_dpp v178, v2 row_shr:1 row_mask:0xf bank_mask:0xf
	v_mov_b32_dpp v179, v3 row_shr:1 row_mask:0xf bank_mask:0xf
	v_pk_fma_f32 v[228:229], v[96:97], v[172:173], v[228:229]
	v_pk_fma_f32 v[230:231], v[98:99], v[174:175], v[230:231]
	v_pk_fma_f32 v[232:233], v[112:113], v[176:177], v[232:233]
	v_pk_fma_f32 v[234:235], v[114:115], v[178:179], v[234:235]
	v_pk_mul_f32 v[216:217], v[228:229], v[220:221]
	v_pk_mul_f32 v[218:219], v[230:231], v[220:221]
	v_exp_f32_e32 v216, v216
	v_exp_f32_e32 v217, v217
	v_exp_f32_e32 v218, v218
	v_exp_f32_e32 v219, v219
	v_pk_add_f32 v[216:217], v[216:217], v[222:223]
	v_pk_add_f32 v[218:219], v[218:219], v[222:223]
	v_rcp_f32_e32 v216, v216
	v_rcp_f32_e32 v217, v217
	v_rcp_f32_e32 v218, v218
	v_rcp_f32_e32 v219, v219
	v_pk_mul_f32 v[228:229], v[228:229], v[216:217]
	v_pk_mul_f32 v[230:231], v[230:231], v[218:219]
	v_pk_mul_f32 v[228:229], v[232:233], v[228:229]
	v_pk_mul_f32 v[230:231], v[234:235], v[230:231]
	s_add_u32 s8, s90, 0xb0000
	s_addc_u32 s9, s91, 0
	v_cvt_pk_bf16_f32 v224, v228, v229
	v_cvt_pk_bf16_f32 v225, v230, v231
	global_store_dwordx2 v237, v[224:225], s[8:9] offset:8
	v_pk_fma_f32 v[228:229], v[104:105], v[12:13], v[108:109]
	v_pk_fma_f32 v[230:231], v[106:107], v[14:15], v[110:111]
	v_pk_fma_f32 v[232:233], v[120:121], v[8:9], v[124:125]
	v_pk_fma_f32 v[234:235], v[122:123], v[10:11], v[126:127]
	v_pk_fma_f32 v[228:229], v[100:101], v[20:21], v[228:229]
	v_pk_fma_f32 v[230:231], v[102:103], v[22:23], v[230:231]
	v_pk_fma_f32 v[232:233], v[116:117], v[16:17], v[232:233]
	v_pk_fma_f32 v[234:235], v[118:119], v[18:19], v[234:235]
	v_pk_fma_f32 v[228:229], v[96:97], v[28:29], v[228:229]
	v_pk_fma_f32 v[230:231], v[98:99], v[30:31], v[230:231]
	v_pk_fma_f32 v[232:233], v[112:113], v[24:25], v[232:233]
	v_pk_fma_f32 v[234:235], v[114:115], v[26:27], v[234:235]
	v_pk_mul_f32 v[216:217], v[228:229], v[220:221]
	v_pk_mul_f32 v[218:219], v[230:231], v[220:221]
	v_exp_f32_e32 v216, v216
	v_exp_f32_e32 v217, v217
	v_exp_f32_e32 v218, v218
	v_exp_f32_e32 v219, v219
	v_pk_add_f32 v[216:217], v[216:217], v[222:223]
	v_pk_add_f32 v[218:219], v[218:219], v[222:223]
	v_rcp_f32_e32 v216, v216
	v_rcp_f32_e32 v217, v217
	v_rcp_f32_e32 v218, v218
	v_rcp_f32_e32 v219, v219
	v_pk_mul_f32 v[228:229], v[228:229], v[216:217]
	v_pk_mul_f32 v[230:231], v[230:231], v[218:219]
	v_pk_mul_f32 v[228:229], v[232:233], v[228:229]
	v_pk_mul_f32 v[230:231], v[234:235], v[230:231]
	s_add_u32 s8, s90, 0xb1600
	s_addc_u32 s9, s91, 0
	v_cvt_pk_bf16_f32 v224, v228, v229
	v_cvt_pk_bf16_f32 v225, v230, v231
	global_store_dwordx2 v237, v[224:225], s[8:9] offset:8
	v_pk_fma_f32 v[228:229], v[104:105], v[4:5], v[108:109]
	v_pk_fma_f32 v[230:231], v[106:107], v[6:7], v[110:111]
	v_pk_fma_f32 v[232:233], v[120:121], v[0:1], v[124:125]
	v_pk_fma_f32 v[234:235], v[122:123], v[2:3], v[126:127]
	v_pk_fma_f32 v[228:229], v[100:101], v[12:13], v[228:229]
	v_pk_fma_f32 v[230:231], v[102:103], v[14:15], v[230:231]
	v_pk_fma_f32 v[232:233], v[116:117], v[8:9], v[232:233]
	v_pk_fma_f32 v[234:235], v[118:119], v[10:11], v[234:235]
	v_pk_fma_f32 v[228:229], v[96:97], v[20:21], v[228:229]
	v_pk_fma_f32 v[230:231], v[98:99], v[22:23], v[230:231]
	v_pk_fma_f32 v[232:233], v[112:113], v[16:17], v[232:233]
	v_pk_fma_f32 v[234:235], v[114:115], v[18:19], v[234:235]
	v_pk_mul_f32 v[216:217], v[228:229], v[220:221]
	v_pk_mul_f32 v[218:219], v[230:231], v[220:221]
	v_exp_f32_e32 v216, v216
	v_exp_f32_e32 v217, v217
	v_exp_f32_e32 v218, v218
	v_exp_f32_e32 v219, v219
	v_pk_add_f32 v[216:217], v[216:217], v[222:223]
	v_pk_add_f32 v[218:219], v[218:219], v[222:223]
	v_rcp_f32_e32 v216, v216
	v_rcp_f32_e32 v217, v217
	v_rcp_f32_e32 v218, v218
	v_rcp_f32_e32 v219, v219
	v_pk_mul_f32 v[228:229], v[228:229], v[216:217]
	v_pk_mul_f32 v[230:231], v[230:231], v[218:219]
	v_pk_mul_f32 v[228:229], v[232:233], v[228:229]
	v_pk_mul_f32 v[230:231], v[234:235], v[230:231]
	s_add_u32 s8, s90, 0xb2c00
	s_addc_u32 s9, s91, 0
	v_cvt_pk_bf16_f32 v224, v228, v229
	v_cvt_pk_bf16_f32 v225, v230, v231
	global_store_dwordx2 v237, v[224:225], s[8:9] offset:8
	v_mov_b32_dpp v180, v28 row_shl:1 row_mask:0xf bank_mask:0xf
	v_mov_b32_dpp v181, v29 row_shl:1 row_mask:0xf bank_mask:0xf
	v_mov_b32_dpp v182, v30 row_shl:1 row_mask:0xf bank_mask:0xf
	v_mov_b32_dpp v183, v31 row_shl:1 row_mask:0xf bank_mask:0xf
	v_mov_b32_dpp v184, v24 row_shl:1 row_mask:0xf bank_mask:0xf
	v_mov_b32_dpp v185, v25 row_shl:1 row_mask:0xf bank_mask:0xf
	v_mov_b32_dpp v186, v26 row_shl:1 row_mask:0xf bank_mask:0xf
	v_mov_b32_dpp v187, v27 row_shl:1 row_mask:0xf bank_mask:0xf
	v_pk_fma_f32 v[228:229], v[104:105], v[180:181], v[108:109]
	v_pk_fma_f32 v[230:231], v[106:107], v[182:183], v[110:111]
	v_pk_fma_f32 v[232:233], v[120:121], v[184:185], v[124:125]
	v_pk_fma_f32 v[234:235], v[122:123], v[186:187], v[126:127]
	v_pk_fma_f32 v[228:229], v[100:101], v[4:5], v[228:229]
	v_pk_fma_f32 v[230:231], v[102:103], v[6:7], v[230:231]
	v_pk_fma_f32 v[232:233], v[116:117], v[0:1], v[232:233]
	v_pk_fma_f32 v[234:235], v[118:119], v[2:3], v[234:235]
	v_pk_fma_f32 v[228:229], v[96:97], v[12:13], v[228:229]
	v_pk_fma_f32 v[230:231], v[98:99], v[14:15], v[230:231]
	v_pk_fma_f32 v[232:233], v[112:113], v[8:9], v[232:233]
	v_pk_fma_f32 v[234:235], v[114:115], v[10:11], v[234:235]
	v_pk_mul_f32 v[216:217], v[228:229], v[220:221]
	v_pk_mul_f32 v[218:219], v[230:231], v[220:221]
	v_exp_f32_e32 v216, v216
	v_exp_f32_e32 v217, v217
	v_exp_f32_e32 v218, v218
	v_exp_f32_e32 v219, v219
	v_pk_add_f32 v[216:217], v[216:217], v[222:223]
	v_pk_add_f32 v[218:219], v[218:219], v[222:223]
	v_rcp_f32_e32 v216, v216
	v_rcp_f32_e32 v217, v217
	v_rcp_f32_e32 v218, v218
	v_rcp_f32_e32 v219, v219
	v_pk_mul_f32 v[228:229], v[228:229], v[216:217]
	v_pk_mul_f32 v[230:231], v[230:231], v[218:219]
	v_pk_mul_f32 v[228:229], v[232:233], v[228:229]
	v_pk_mul_f32 v[230:231], v[234:235], v[230:231]
	s_add_u32 s8, s90, 0xb4200
	s_addc_u32 s9, s91, 0
	v_cvt_pk_bf16_f32 v224, v228, v229
	v_cvt_pk_bf16_f32 v225, v230, v231
	global_store_dwordx2 v237, v[224:225], s[8:9] offset:8
	s_andn2_b64 vcc, exec, s[82:83]
	s_mov_b64 s[4:5], -1
	s_cbranch_vccnz .LBB0_43
	s_andn2_b64 vcc, exec, s[88:89]
	s_cbranch_vccnz .LBB0_42
	s_barrier
	s_branch .LBB0_42
